# v29 + final combine+LayerNorm phase: gamma/beta loads hoisted out of the token loop (no per-chunk load + vmcnt(0) ladder)
# speedup vs baseline: 1.0214x; 1.0036x over previous
.LBB0_1409:
	s_or_b64 exec, exec, s[0:1]
	s_and_b64 vcc, exec, s[70:71]
	s_waitcnt lgkmcnt(0)
	s_barrier
	s_cbranch_vccz .LBB0_1412
	v_mbcnt_hi_u32_b32 v2, -1, v186
	v_and_b32_e32 v3, 64, v2
	v_add_u32_e32 v3, 64, v3
	v_xor_b32_e32 v4, 1, v2
	v_cmp_lt_i32_e32 vcc, v4, v3
	v_ashrrev_i32_e32 v161, 31, v160
	v_readlane_b32 s0, v234, 23
	v_cndmask_b32_e32 v4, v2, v4, vcc
	v_lshlrev_b32_e32 v12, 2, v4
	v_xor_b32_e32 v4, 2, v2
	v_cmp_lt_i32_e32 vcc, v4, v3
	v_readlane_b32 s1, v234, 24
	v_readlane_b32 s2, v234, 25
	v_cndmask_b32_e32 v4, v2, v4, vcc
	v_lshlrev_b32_e32 v13, 2, v4
	v_xor_b32_e32 v4, 4, v2
	v_cmp_lt_i32_e32 vcc, v4, v3
	v_readlane_b32 s3, v234, 26
	v_readlane_b32 s11, v234, 34
	v_cndmask_b32_e32 v4, v2, v4, vcc
	v_lshlrev_b32_e32 v14, 2, v4
	v_xor_b32_e32 v4, 8, v2
	v_cmp_lt_i32_e32 vcc, v4, v3
	s_ashr_i32 s47, s46, 31
	v_readlane_b32 s4, v234, 27
	v_cndmask_b32_e32 v4, v2, v4, vcc
	v_lshlrev_b32_e32 v15, 2, v4
	v_xor_b32_e32 v4, 16, v2
	v_cmp_lt_i32_e32 vcc, v4, v3
	v_readlane_b32 s14, v234, 37
	s_lshl_b32 s11, s82, 4
	v_cndmask_b32_e32 v4, v2, v4, vcc
	v_lshlrev_b32_e32 v16, 2, v4
	v_xor_b32_e32 v4, 32, v2
	v_cmp_lt_i32_e32 vcc, v4, v3
	v_readlane_b32 s5, v234, 28
	v_readlane_b32 s15, v234, 38
	v_cndmask_b32_e32 v2, v2, v4, vcc
	v_lshlrev_b32_e32 v17, 2, v2
	v_lshlrev_b64 v[2:3], 4, v[160:161]
	v_lshl_add_u64 v[4:5], s[0:1], 0, v[2:3]
	s_mov_b64 s[0:1], 0x1000
	v_lshl_add_u64 v[6:7], s[2:3], 0, v[2:3]
	v_lshl_add_u64 v[4:5], v[4:5], 0, s[0:1]
	v_lshl_add_u64 v[6:7], v[6:7], 0, s[0:1]
	v_readlane_b32 s0, v234, 0
	v_readlane_b32 s1, v234, 1
	s_lshl_b32 s0, s0, 4
	s_lshl_b32 s1, s86, 1
	s_add_i32 s2, s0, s1
	s_lshl_b64 s[0:1], s[46:47], 12
	s_add_u32 s4, s14, s0
	v_readlane_b32 s6, v234, 29
	v_readlane_b32 s7, v234, 30
	s_addc_u32 s5, s15, s1
	s_ashr_i32 s81, s80, 31
	v_readlane_b32 s8, v234, 31
	s_lshl_b64 s[6:7], s[80:81], 12
	v_readlane_b32 s9, v234, 32
	v_readlane_b32 s10, v234, 33
	v_readlane_b32 s12, v234, 35
	v_readlane_b32 s13, v234, 36
	s_add_u32 s8, s84, s0
	v_lshl_add_u64 v[0:1], v[160:161], 3, s[68:69]
	s_addc_u32 s9, s85, s1
	v_mov_b32_e32 v18, 0
	s_mov_b32 s12, 0x10400000
	s_mov_b32 s10, 0x3fb504f3
	v_mov_b32_e32 v19, 0x3727c5ac
	s_mov_b32 s13, 0xf800000
	v_mov_b32_e32 v20, 0x260
	global_load_dwordx4 v[100:103], v[4:5], off
	global_load_dwordx4 v[104:107], v[4:5], off offset:1024
	global_load_dwordx4 v[108:111], v[4:5], off offset:2048
	global_load_dwordx4 v[112:115], v[4:5], off offset:3072
	global_load_dwordx4 v[116:119], v[6:7], off
	global_load_dwordx4 v[120:123], v[6:7], off offset:1024
	global_load_dwordx4 v[124:127], v[6:7], off offset:2048
	global_load_dwordx4 v[128:131], v[6:7], off offset:3072
	s_waitcnt vmcnt(0)
.LBB0_1411:
	s_ashr_i32 s3, s2, 31
	v_lshl_add_u64 v[8:9], s[8:9], 0, v[2:3]
	s_lshl_b64 s[0:1], s[2:3], 2
	v_add_co_u32_e32 v8, vcc, s12, v8
	s_add_u32 s14, s50, s0
	s_nop 0
	v_addc_co_u32_e32 v9, vcc, 0, v9, vcc
	s_addc_u32 s15, s51, s1
	global_load_dwordx4 v[30:33], v[8:9], off nt
	global_load_dwordx4 v[34:37], v[8:9], off offset:1024 nt
	global_load_dwordx4 v[38:41], v[8:9], off offset:2048 nt
	global_load_dwordx4 v[42:45], v[8:9], off offset:3072 nt
	s_add_u32 s0, s54, s0
	global_load_dwordx2 v[8:9], v18, s[14:15]
	s_addc_u32 s1, s55, s1
	global_load_dwordx2 v[46:47], v18, s[0:1]
	v_lshl_add_u64 v[10:11], s[4:5], 0, v[2:3]
	s_add_i32 s46, s46, s80
	s_add_i32 s2, s2, s11
	s_add_u32 s4, s4, s6
	s_addc_u32 s5, s5, s7
	s_add_u32 s8, s8, s6
	s_addc_u32 s9, s9, s7
	s_cmpk_lt_i32 s46, 0x4000
	s_waitcnt vmcnt(1)
	v_ashrrev_i32_e32 v49, 31, v8
	v_mov_b32_e32 v48, v8
	v_ashrrev_i32_e32 v51, 31, v9
	v_mov_b32_e32 v50, v9
	v_lshlrev_b64 v[8:9], 11, v[48:49]
	v_lshlrev_b64 v[48:49], 11, v[50:51]
	v_lshl_add_u64 v[8:9], v[0:1], 0, v[8:9]
	v_lshl_add_u64 v[48:49], v[0:1], 0, v[48:49]
	global_load_dwordx2 v[50:51], v[8:9], off nt
	global_load_dwordx2 v[52:53], v[48:49], off nt
	global_load_dwordx2 v[54:55], v[8:9], off offset:512 nt
	global_load_dwordx2 v[56:57], v[48:49], off offset:512 nt
	global_load_dwordx2 v[58:59], v[8:9], off offset:1024 nt
	global_load_dwordx2 v[60:61], v[48:49], off offset:1024 nt
	global_load_dwordx2 v[62:63], v[8:9], off offset:1536 nt
	global_load_dwordx2 v[64:65], v[48:49], off offset:1536 nt
	s_waitcnt vmcnt(7)
	v_lshlrev_b32_e32 v8, 16, v50
	v_and_b32_e32 v9, 0xffff0000, v50
	v_lshlrev_b32_e32 v48, 16, v51
	v_and_b32_e32 v49, 0xffff0000, v51
	s_waitcnt vmcnt(6)
	v_lshlrev_b32_e32 v50, 16, v52
	v_and_b32_e32 v51, 0xffff0000, v52
	v_lshlrev_b32_e32 v52, 16, v53
	v_and_b32_e32 v53, 0xffff0000, v53
	s_waitcnt vmcnt(4)
	v_lshlrev_b32_e32 v68, 16, v56
	v_and_b32_e32 v69, 0xffff0000, v56
	v_lshlrev_b32_e32 v56, 16, v57
	v_and_b32_e32 v57, 0xffff0000, v57
	v_lshlrev_b32_e32 v66, 16, v54
	v_and_b32_e32 v67, 0xffff0000, v54
	v_lshlrev_b32_e32 v54, 16, v55
	v_and_b32_e32 v55, 0xffff0000, v55
	s_waitcnt vmcnt(2)
	v_lshlrev_b32_e32 v72, 16, v60
	v_and_b32_e32 v73, 0xffff0000, v60
	v_lshlrev_b32_e32 v60, 16, v61
	v_and_b32_e32 v61, 0xffff0000, v61
	s_waitcnt vmcnt(0)
	v_lshlrev_b32_e32 v76, 16, v64
	v_and_b32_e32 v77, 0xffff0000, v64
	v_lshlrev_b32_e32 v64, 16, v65
	v_and_b32_e32 v65, 0xffff0000, v65
	v_pk_mul_f32 v[52:53], v[46:47], v[52:53] op_sel:[1,0]
	v_pk_mul_f32 v[50:51], v[46:47], v[50:51] op_sel:[1,0]
	v_pk_mul_f32 v[56:57], v[46:47], v[56:57] op_sel:[1,0]
	v_pk_mul_f32 v[68:69], v[46:47], v[68:69] op_sel:[1,0]
	v_lshlrev_b32_e32 v70, 16, v58
	v_and_b32_e32 v71, 0xffff0000, v58
	v_lshlrev_b32_e32 v58, 16, v59
	v_and_b32_e32 v59, 0xffff0000, v59
	v_lshlrev_b32_e32 v74, 16, v62
	v_and_b32_e32 v75, 0xffff0000, v62
	v_lshlrev_b32_e32 v62, 16, v63
	v_and_b32_e32 v63, 0xffff0000, v63
	v_pk_mul_f32 v[60:61], v[46:47], v[60:61] op_sel:[1,0]
	v_pk_mul_f32 v[72:73], v[46:47], v[72:73] op_sel:[1,0]
	v_pk_mul_f32 v[64:65], v[46:47], v[64:65] op_sel:[1,0]
	v_pk_mul_f32 v[76:77], v[46:47], v[76:77] op_sel:[1,0]
	v_pk_fma_f32 v[8:9], v[46:47], v[8:9], v[50:51] op_sel_hi:[0,1,1]
	v_pk_fma_f32 v[48:49], v[46:47], v[48:49], v[52:53] op_sel_hi:[0,1,1]
	v_pk_fma_f32 v[50:51], v[46:47], v[66:67], v[68:69] op_sel_hi:[0,1,1]
	v_pk_fma_f32 v[52:53], v[46:47], v[54:55], v[56:57] op_sel_hi:[0,1,1]
	v_pk_fma_f32 v[54:55], v[46:47], v[70:71], v[72:73] op_sel_hi:[0,1,1]
	v_pk_fma_f32 v[56:57], v[46:47], v[58:59], v[60:61] op_sel_hi:[0,1,1]
	v_pk_fma_f32 v[58:59], v[46:47], v[74:75], v[76:77] op_sel_hi:[0,1,1]
	v_pk_fma_f32 v[46:47], v[46:47], v[62:63], v[64:65] op_sel_hi:[0,1,1]
	v_pk_fma_f32 v[32:33], v[32:33], s[10:11], v[48:49] op_sel_hi:[1,0,1]
	v_pk_fma_f32 v[8:9], v[30:31], s[10:11], v[8:9] op_sel_hi:[1,0,1]
	v_pk_fma_f32 v[30:31], v[36:37], s[10:11], v[52:53] op_sel_hi:[1,0,1]
	v_pk_fma_f32 v[34:35], v[34:35], s[10:11], v[50:51] op_sel_hi:[1,0,1]
	v_pk_fma_f32 v[36:37], v[40:41], s[10:11], v[56:57] op_sel_hi:[1,0,1]
	v_pk_fma_f32 v[40:41], v[44:45], s[10:11], v[46:47] op_sel_hi:[1,0,1]
	v_pk_mov_b32 v[44:45], v[8:9], v[32:33] op_sel:[1,0]
	v_mov_b32_e32 v46, v8
	v_mov_b32_e32 v47, v33
	v_pk_mov_b32 v[48:49], v[34:35], v[30:31] op_sel:[1,0]
	v_mov_b32_e32 v50, v34
	v_mov_b32_e32 v51, v31
	v_pk_add_f32 v[44:45], v[44:45], v[46:47]
	v_pk_add_f32 v[46:47], v[48:49], v[50:51]
	v_pk_fma_f32 v[38:39], v[38:39], s[10:11], v[54:55] op_sel_hi:[1,0,1]
	v_pk_fma_f32 v[42:43], v[42:43], s[10:11], v[58:59] op_sel_hi:[1,0,1]
	v_add_f32_e32 v21, v44, v45
	v_pk_add_f32 v[44:45], v[46:47], v[46:47] op_sel:[0,1] op_sel_hi:[1,0]
	v_add_f32_e32 v52, v38, v39
	v_add_f32_e32 v54, v36, v37
	v_mov_b32_e32 v57, v42
	v_mov_b32_e32 v53, v40
	v_mov_b32_e32 v55, v41
	v_add_f32_e32 v56, 0, v21
	v_mov_b32_e32 v45, v43
	v_pk_add_f32 v[48:49], v[52:53], v[54:55]
	v_pk_add_f32 v[44:45], v[56:57], v[44:45]
	s_nop 0
	v_pk_add_f32 v[44:45], v[44:45], v[48:49]
	s_nop 0
	v_add_f32_e32 v21, v44, v45
	ds_bpermute_b32 v44, v12, v21
	s_waitcnt lgkmcnt(0)
	v_add_f32_e32 v21, v21, v44
	ds_bpermute_b32 v44, v13, v21
	s_waitcnt lgkmcnt(0)
	v_add_f32_e32 v21, v21, v44
	ds_bpermute_b32 v44, v14, v21
	s_waitcnt lgkmcnt(0)
	v_add_f32_e32 v21, v21, v44
	ds_bpermute_b32 v44, v15, v21
	s_waitcnt lgkmcnt(0)
	v_add_f32_e32 v21, v21, v44
	ds_bpermute_b32 v44, v16, v21
	s_waitcnt lgkmcnt(0)
	v_add_f32_e32 v21, v21, v44
	ds_bpermute_b32 v44, v17, v21
	s_waitcnt lgkmcnt(0)
	v_add_f32_e32 v21, v21, v44
	v_fmamk_f32 v9, v21, 0xba800000, v9
	v_fmac_f32_e32 v8, 0xba800000, v21
	v_fmamk_f32 v33, v21, 0xba800000, v33
	v_fmac_f32_e32 v32, 0xba800000, v21
	v_fmamk_f32 v35, v21, 0xba800000, v35
	v_fmac_f32_e32 v34, 0xba800000, v21
	v_fmamk_f32 v31, v21, 0xba800000, v31
	v_fmac_f32_e32 v30, 0xba800000, v21
	v_pk_mul_f32 v[44:45], v[32:33], v[32:33]
	v_pk_mul_f32 v[46:47], v[8:9], v[8:9]
	v_pk_mul_f32 v[48:49], v[30:31], v[30:31]
	v_pk_mul_f32 v[50:51], v[34:35], v[34:35]
	v_fmac_f32_e32 v38, 0xba800000, v21
	v_fmac_f32_e32 v36, 0xba800000, v21
	v_pk_mov_b32 v[56:57], v[46:47], v[44:45] op_sel:[1,0]
	v_mov_b32_e32 v47, v45
	v_pk_mov_b32 v[44:45], v[50:51], v[48:49] op_sel:[1,0]
	v_mov_b32_e32 v51, v49
	v_fmamk_f32 v39, v21, 0xba800000, v39
	v_fmamk_f32 v37, v21, 0xba800000, v37
	v_mul_f32_e32 v52, v38, v38
	v_mul_f32_e32 v54, v36, v36
	v_pk_add_f32 v[46:47], v[56:57], v[46:47]
	v_pk_add_f32 v[44:45], v[44:45], v[50:51]
	v_fmamk_f32 v41, v21, 0xba800000, v41
	v_fmac_f32_e32 v40, 0xba800000, v21
	v_fmamk_f32 v43, v21, 0xba800000, v43
	v_fmac_f32_e32 v42, 0xba800000, v21
	v_pk_fma_f32 v[48:49], v[38:39], v[38:39], v[52:53] op_sel_hi:[1,1,0]
	v_pk_fma_f32 v[52:53], v[36:37], v[36:37], v[54:55] op_sel_hi:[1,1,0]
	v_pk_add_f32 v[46:47], v[46:47], v[46:47] op_sel_hi:[0,1]
	v_pk_add_f32 v[44:45], v[44:45], v[44:45] op_sel_hi:[0,1]
	v_mul_f32_e32 v48, v42, v42
	v_mul_f32_e32 v52, v43, v43
	v_mul_f32_e32 v46, v40, v40
	v_mul_f32_e32 v44, v41, v41
	v_pk_add_f32 v[48:49], v[48:49], v[52:53]
	v_pk_add_f32 v[44:45], v[46:47], v[44:45]
	s_nop 0
	v_pk_add_f32 v[44:45], v[48:49], v[44:45]
	s_nop 0
	v_add_f32_e32 v21, v44, v45
	ds_bpermute_b32 v44, v12, v21
	s_waitcnt lgkmcnt(0)
	v_add_f32_e32 v21, v21, v44
	ds_bpermute_b32 v44, v13, v21
	s_waitcnt lgkmcnt(0)
	v_add_f32_e32 v21, v21, v44
	ds_bpermute_b32 v44, v14, v21
	s_waitcnt lgkmcnt(0)
	v_add_f32_e32 v21, v21, v44
	ds_bpermute_b32 v44, v15, v21
	s_waitcnt lgkmcnt(0)
	v_add_f32_e32 v21, v21, v44
	ds_bpermute_b32 v44, v16, v21
	s_waitcnt lgkmcnt(0)
	v_add_f32_e32 v21, v21, v44
	ds_bpermute_b32 v44, v17, v21
	s_waitcnt lgkmcnt(0)
	v_add_f32_e32 v21, v21, v44
	v_fmamk_f32 v21, v21, 0x3a800000, v19
	v_mul_f32_e32 v44, 0x4f800000, v21
	v_cmp_gt_f32_e32 vcc, s13, v21
	s_nop 1
	v_cndmask_b32_e32 v21, v21, v44, vcc
	v_sqrt_f32_e32 v44, v21
	s_nop 0
	v_add_u32_e32 v45, -1, v44
	v_add_u32_e32 v46, 1, v44
	v_fma_f32 v47, -v45, v44, v21
	v_fma_f32 v48, -v46, v44, v21
	v_cmp_ge_f32_e64 s[0:1], 0, v47
	s_nop 1
	v_cndmask_b32_e64 v44, v44, v45, s[0:1]
	v_cmp_lt_f32_e64 s[0:1], 0, v48
	s_nop 1
	v_cndmask_b32_e64 v44, v44, v46, s[0:1]
	v_mul_f32_e32 v45, 0x37800000, v44
	v_cndmask_b32_e32 v44, v44, v45, vcc
	v_cmp_class_f32_e32 vcc, v21, v20
	s_nop 1
	v_cndmask_b32_e32 v21, v44, v21, vcc
	v_div_scale_f32 v44, s[0:1], v21, v21, 1.0
	v_rcp_f32_e32 v46, v44
	v_div_scale_f32 v45, vcc, 1.0, v21, 1.0
	v_fma_f32 v47, -v44, v46, 1.0
	v_fmac_f32_e32 v46, v47, v46
	v_mul_f32_e32 v47, v45, v46
	v_fma_f32 v48, -v44, v47, v45
	v_fmac_f32_e32 v47, v48, v46
	v_fma_f32 v44, -v44, v47, v45
	v_div_fmas_f32 v44, v44, v46, v47
	v_div_fixup_f32 v44, v44, v21, 1.0
	v_pk_mul_f32 v[8:9], v[8:9], v[44:45] op_sel_hi:[1,0]
	v_pk_mul_f32 v[32:33], v[32:33], v[44:45] op_sel_hi:[1,0]
	v_pk_fma_f32 v[22:23], v[100:101], v[8:9], v[116:117]
	v_pk_fma_f32 v[24:25], v[102:103], v[32:33], v[118:119]
	global_store_dwordx4 v[10:11], v[22:25], off nt
	s_nop 0
	v_pk_mul_f32 v[8:9], v[30:31], v[44:45] op_sel_hi:[1,0]
	v_pk_mul_f32 v[30:31], v[34:35], v[44:45] op_sel_hi:[1,0]
	v_pk_fma_f32 v[24:25], v[106:107], v[8:9], v[122:123]
	v_pk_fma_f32 v[22:23], v[104:105], v[30:31], v[120:121]
	global_store_dwordx4 v[10:11], v[22:25], off offset:1024 nt
	s_nop 0
	v_pk_mul_f32 v[8:9], v[36:37], v[44:45] op_sel_hi:[1,0]
	v_pk_mul_f32 v[30:31], v[38:39], v[44:45] op_sel_hi:[1,0]
	v_pk_fma_f32 v[24:25], v[110:111], v[8:9], v[126:127]
	v_pk_fma_f32 v[22:23], v[108:109], v[30:31], v[124:125]
	global_store_dwordx4 v[10:11], v[22:25], off offset:2048 nt
	s_nop 0
	v_pk_mul_f32 v[8:9], v[40:41], v[44:45] op_sel_hi:[1,0]
	v_pk_mul_f32 v[30:31], v[42:43], v[44:45] op_sel_hi:[1,0]
	v_pk_fma_f32 v[24:25], v[114:115], v[8:9], v[130:131]
	v_pk_fma_f32 v[22:23], v[112:113], v[30:31], v[128:129]
	global_store_dwordx4 v[10:11], v[22:25], off offset:3072 nt
	s_cbranch_scc1 .LBB0_1411
